# speedup vs baseline: 1.1095x; 1.0025x over previous
; #define MFMA32(a, b, c) __builtin_amdgcn_mfma_f32_32x32x16_bf16((a), (b), (c), 0, 0, 0)
; template <int MODE>
; DI void attn_item(const u16* __restrict__ Qp, const u16* __restrict__ Kp, const u16* __restrict__ VTp, int q0,
;                   int kt_lo, int kt_hi, u16* __restrict__ Op, int os, float* __restrict__ lsep, int ls, char* lds, int tid) {
;     ...
;     for (int ks = 0; ks < NKS; ks++)
; #pragma unroll
;       for (int mt = 0; mt < NMT; mt++) {
;         const bf16x8 kf = *(const bf16x8*)(Ks + (mt * 32 + c) * KROW + (ks * 16 + h * 8) * 2);
;         st[mt] = MFMA32(kf, qf[ks], st[mt]);
;       }
;     if (NMT == 1) {
;       __builtin_amdgcn_sched_group_barrier(0x100, 3, 0);
; #pragma unroll
;       for (int ks = 0; ks < NKS - 3; ks++) {
;         __builtin_amdgcn_sched_group_barrier(0x008, 1, 0);
;         __builtin_amdgcn_sched_group_barrier(0x100, 1, 0);
;       }
;       __builtin_amdgcn_sched_group_barrier(0x008, 3, 0);
;     }
;     const int kb = kt * KT + 4 * h;
;     if (MODE == 0 && kt * KT + (KT - 1) <= q0 + wave * 32) {
;       float mx = st[0][0];
; #pragma unroll
;       for (int mt = 0; mt < NMT; mt++)
; #pragma unroll
;         for (int r = 0; r < 16; r++) mx = fmaxf(mx, st[mt][r]);
;       mx = fmaxf(mx, __shfl_xor(mx, 32));
;       const float m_new = fmaxf(m_run, mx);
;       const float alpha = __builtin_amdgcn_exp2f(m_run - m_new);
;       m_run = m_new;
;       float psum = 0.f;
; #pragma unroll
;       for (int mt = 0; mt < NMT; mt++)
; #pragma unroll
;         for (int r = 0; r < 16; r++) {
;           const float p = __builtin_amdgcn_exp2f(st[mt][r] - m_new);
;           psum += p;
;           st[mt][r] = p;
;         }
;       l_run = l_run * alpha + psum;
.LBB0_467:
	s_bitcmp1_b32 s42, 0
	s_cselect_b32 s11, 0x5a00, 0
	v_add3_u32 v200, s11, v210, v207
	v_add3_u32 v252, s11, v156, v208
	ds_read_b128 v[64:67], v200
	ds_read_b128 v[220:223], v200 offset:32
	ds_read_b128 v[236:239], v200 offset:64
	ds_read_b128 v[240:243], v200 offset:96
	ds_read_b128 v[244:247], v200 offset:128
	ds_read_b128 v[248:251], v200 offset:160
	s_add_i32 s14, s10, -1
	v_cmp_le_i32_e32 vcc, s14, v216
	s_setprio 1
	s_waitcnt lgkmcnt(5)
	v_mfma_f32_32x32x16_bf16 v[64:79], v[64:67], v[80:83], 0
	s_waitcnt lgkmcnt(4)
	v_mfma_f32_32x32x16_bf16 v[64:79], v[220:223], v[84:87], v[64:79]
	ds_read_b128 v[220:223], v200 offset:192
	s_waitcnt lgkmcnt(4)
	v_mfma_f32_32x32x16_bf16 v[64:79], v[236:239], v[88:91], v[64:79]
	ds_read_b128 v[236:239], v200 offset:224
	s_waitcnt lgkmcnt(4)
	v_mfma_f32_32x32x16_bf16 v[64:79], v[240:243], v[92:95], v[64:79]
	ds_read_b128 v[240:243], v200 offset:256
	s_waitcnt lgkmcnt(4)
	v_mfma_f32_32x32x16_bf16 v[64:79], v[244:247], v[96:99], v[64:79]
	ds_read_b128 v[244:247], v200 offset:288
	s_waitcnt lgkmcnt(4)
	v_mfma_f32_32x32x16_bf16 v[64:79], v[248:251], v[100:103], v[64:79]
	ds_read_b128 v[248:251], v200 offset:320
	s_waitcnt lgkmcnt(4)
	v_mfma_f32_32x32x16_bf16 v[64:79], v[220:223], v[104:107], v[64:79]
	ds_read_b128 v[220:223], v200 offset:352
	s_waitcnt lgkmcnt(4)
	v_mfma_f32_32x32x16_bf16 v[64:79], v[236:239], v[108:111], v[64:79]
	s_waitcnt lgkmcnt(3)
	v_mfma_f32_32x32x16_bf16 v[64:79], v[240:243], v[112:115], v[64:79]
	s_waitcnt lgkmcnt(2)
	v_mfma_f32_32x32x16_bf16 v[64:79], v[244:247], v[116:119], v[64:79]
	s_waitcnt lgkmcnt(1)
	v_mfma_f32_32x32x16_bf16 v[64:79], v[248:251], v[120:123], v[64:79]
	s_waitcnt lgkmcnt(0)
	v_mfma_f32_32x32x16_bf16 v[64:79], v[220:223], v[124:127], v[64:79]
	s_setprio 0
	ds_read_b64 v[236:237], v252 offset:12800
	ds_read_b64 v[238:239], v252 offset:12816
	ds_read_b64 v[240:241], v252 offset:15360
	ds_read_b64 v[242:243], v252 offset:15376
	ds_read_b64 v[244:245], v252 offset:17920
	ds_read_b64 v[246:247], v252 offset:17936
	ds_read_b64 v[248:249], v252 offset:20480
	ds_read_b64 v[250:251], v252 offset:20496
	s_and_saveexec_b64 s[14:15], vcc
	s_xor_b64 s[14:15], exec, s[14:15]
	s_cbranch_execz .LBB0_469
	s_nop 8
	v_max_f32_e32 v200, v65, v65
	v_max_f32_e32 v201, v64, v64
	v_max_f32_e32 v200, v201, v200
	v_max3_f32 v200, v200, v66, v67
	v_max3_f32 v200, v200, v68, v69
	v_max3_f32 v200, v200, v70, v71
	v_max3_f32 v200, v200, v72, v73
	v_max3_f32 v200, v200, v74, v75
	v_max3_f32 v200, v200, v76, v77
	v_max3_f32 v200, v200, v78, v79
	v_mov_b32_e32 v201, v200
	s_nop 1
	v_permlane32_swap_b32_e32 v201, v200
	v_max3_f32 v217, v218, v200, v201
	v_sub_f32_e32 v64, v64, v217
	v_exp_f32_e32 v219, v64
	v_sub_f32_e32 v64, v65, v217
	v_exp_f32_e32 v220, v64
	v_sub_f32_e32 v64, v66, v217
	v_exp_f32_e32 v221, v64
	v_sub_f32_e32 v64, v67, v217
	v_exp_f32_e32 v222, v64
	v_sub_f32_e32 v64, v68, v217
	v_exp_f32_e32 v223, v64
	v_sub_f32_e32 v64, v69, v217
	v_exp_f32_e32 v224, v64
	v_sub_f32_e32 v64, v70, v217
	v_exp_f32_e32 v225, v64
	v_sub_f32_e32 v64, v71, v217
	v_exp_f32_e32 v226, v64
	v_sub_f32_e32 v64, v72, v217
	v_exp_f32_e32 v227, v64
	v_sub_f32_e32 v64, v73, v217
	v_exp_f32_e32 v228, v64
	v_sub_f32_e32 v64, v74, v217
	v_exp_f32_e32 v229, v64
	v_sub_f32_e32 v64, v75, v217
	v_exp_f32_e32 v230, v64
	v_sub_f32_e32 v64, v76, v217
	v_exp_f32_e32 v231, v64
	v_sub_f32_e32 v64, v77, v217
	v_exp_f32_e32 v232, v64
	v_sub_f32_e32 v64, v78, v217
	v_exp_f32_e32 v233, v64
	v_sub_f32_e32 v64, v79, v217
	v_exp_f32_e32 v234, v64

; #define MFMA32(a, b, c) __builtin_amdgcn_mfma_f32_32x32x16_bf16((a), (b), (c), 0, 0, 0)
; template <int MODE>
; DI void attn_item(const u16* __restrict__ Qp, const u16* __restrict__ Kp, const u16* __restrict__ VTp, int q0,
;                   int kt_lo, int kt_hi, u16* __restrict__ Op, int os, float* __restrict__ lsep, int ls, char* lds, int tid) {
;     ...
; #pragma unroll
;     for (int s4 = 0; s4 < NS4; s4++) {
;       const int mt = s4 >> 1, r0 = (s4 & 1) * 8;
;       uint4 pw;
;       pw.x = pack2(st[mt][r0 + 0], st[mt][r0 + 1]);
;       pw.y = pack2(st[mt][r0 + 2], st[mt][r0 + 3]);
;       pw.z = pack2(st[mt][r0 + 4], st[mt][r0 + 5]);
;       pw.w = pack2(st[mt][r0 + 6], st[mt][r0 + 7]);
;       const bf16x8 pb = __builtin_bit_cast(bf16x8, pw);
; #pragma unroll
;       for (int dt = 0; dt < 4; dt++) {
;         const char* vr = Vs + (dt * 32 + c) * VROW + (16 * s4 + 4 * h) * 2;
;         const bf16x4 lo = *(const bf16x4*)(vr);
;         const bf16x4 hi = *(const bf16x4*)(vr + 16);
;         const bf16x8 vf = __builtin_shufflevector(lo, hi, 0, 1, 2, 3, 4, 5, 6, 7);
;         ot[dt] = MFMA32(vf, pb, ot[dt]);
;       }
;     }
;     if (MODE == 1) {
;       if (__syncthreads_and(R < -100.f)) break;
;     }
;     if (PF) {
;       if (it + 1 < ntiles) { PF_STORE((it + 1) & 1) }
;       __syncthreads();
.Lp4_noresc:
.Lp4_pv:
	v_cvt_pk_bf16_f32 v67, v225, v226
	s_add_i32 s42, s42, 1
	s_andn2_b64 vcc, exec, s[12:13]
	s_waitcnt lgkmcnt(4)
	s_nop 0
	s_setprio 1
	v_mfma_f32_32x32x16_bf16 v[48:63], v[236:239], v[64:67], v[48:63]
	ds_read_b64 v[236:237], v252 offset:17952
	ds_read_b64 v[238:239], v252 offset:17968
	v_mfma_f32_32x32x16_bf16 v[32:47], v[240:243], v[64:67], v[32:47]
	ds_read_b64 v[240:241], v252 offset:20512
	ds_read_b64 v[242:243], v252 offset:20528
	v_mfma_f32_32x32x16_bf16 v[16:31], v[244:247], v[64:67], v[16:31]
	v_mfma_f32_32x32x16_bf16 v[0:15], v[248:251], v[64:67], v[0:15]
	v_cvt_pk_bf16_f32 v64, v227, v228
	v_cvt_pk_bf16_f32 v65, v229, v230
	v_cvt_pk_bf16_f32 v66, v231, v232
	v_cvt_pk_bf16_f32 v67, v233, v234
	s_waitcnt lgkmcnt(4)
	s_nop 0
	v_mfma_f32_32x32x16_bf16 v[32:47], v[74:77], v[64:67], v[32:47]
	s_waitcnt lgkmcnt(2)
	v_mfma_f32_32x32x16_bf16 v[16:31], v[236:239], v[64:67], v[16:31]
	v_mfma_f32_32x32x16_bf16 v[48:63], v[70:73], v[64:67], v[48:63]
	s_waitcnt lgkmcnt(0)
	v_mfma_f32_32x32x16_bf16 v[0:15], v[240:243], v[64:67], v[0:15]
	s_setprio 0
	s_cbranch_vccnz .LBB0_473
	s_bitcmp1_b32 s42, 0
	s_cselect_b32 s11, 0x5a00, 0
	v_add3_u32 v64, s11, v209, v174
	s_waitcnt vmcnt(4)
	ds_write_b128 v64, v[128:131]
	s_waitcnt vmcnt(3)
	ds_write_b128 v64, v[132:135] offset:128
	s_waitcnt vmcnt(2)
	ds_write_b128 v64, v[136:139] offset:256
	v_add3_u32 v64, s11, v177, v175
	s_waitcnt vmcnt(1)
	ds_write_b128 v64, v[140:143] offset:12800
	s_waitcnt vmcnt(0)
	ds_write_b128 v64, v[144:147] offset:17920
